# GQA attention loop: row-max, scale/sub fma and first-half exps moved from the barrier-delimited VALU-only segment into PV MFMA gaps (register renames into spare VGPRs), counted lgkmcnt waits
# speedup vs baseline: 1.0208x; 1.0070x over previous
; __device__ __forceinline__ int v_st(int k, int c) { const int kk = (k & ~0xC) | ((k & 4) << 1) | ((k & 8) >> 1); return ((kk >> 3) * 4 + (c >> 5)) * 512 + ((kk & 7) * 32 + (c & 31)) * 2; }
; __device__ __forceinline__ int v_rd_base(int lane) { return ((lane & 3) << 3) | (((lane >> 2) & 3) << 6) | (((lane >> 4) & 1) << 5) | (((lane >> 5) & 1) << 8); }
; #define SLOAD(i, k0) do { sr_[i].vs0 = *reinterpret_cast<const bf16x8*>(vptr + (size_t)((k0) + sr) * vstr); \
;     sr_[i].vs1 = *reinterpret_cast<const bf16x8*>(vptr + (size_t)((k0) + 32 + sr) * vstr); \
;     sr_[i].ks0 = *reinterpret_cast<const bf16x8*>(kptr + (size_t)((k0) + sr) * kstr); \
;     sr_[i].ks1 = *reinterpret_cast<const bf16x8*>(kptr + (size_t)((k0) + 32 + sr) * kstr); } while (0)
; #define SWRITE(b, i) do { *(LAS bf16x8*)(V_lds + (b) * SHM_V + vst0) = sr_[i].vs0;          \
;     *(LAS bf16x8*)(V_lds + (b) * SHM_V + vst1) = sr_[i].vs1; const int kc = sc * 2;               \
;     *(LAS bf16x8*)(K_lds + (b) * SHM_K + KSWZ(sr, kc)) = sr_[i].ks0;                       \
;     *(LAS bf16x8*)(K_lds + (b) * SHM_K + KSWZ(32 + sr, kc)) = sr_[i].ks1; } while (0)
; template <int NDQ, int NDV> ...
;     ...
;   float m_reg = -1e30f, l_reg = 0; f32x16 o[NDV]; bf16x8 qr[NDQ];
; #pragma unroll
;   for (int d = 0; d < NDV; ++d) o[d] = f32x16{};
;   const bf16_t* Qw = Qb + (size_t)(wid * 32 + r32) * ldq + hi * 8;
; #pragma unroll
;   for (int d0 = 0; d0 < NDQ; ++d0) qr[d0] = *reinterpret_cast<const bf16x8*>(Qw + d0 * 16);
;   const int sr = tid >> 4, sc = (tid & 15) * 8, vst0 = v_st(sr, sc), vst1 = v_st(32 + sr, sc);
;   const int vb0 = (int)(unsigned)(size_t)V_lds + v_rd_base(lane);
;   struct { bf16x8 vs0, vs1, ks0, ks1; } sr_[2];
;     ...
;   f32x16 pA0, pA1, pB0, pB1; float mnA, mnB, alA, alB; bf16x8 pa0, pa1, pa2, pa3; const int NT = seq / 64;
;   constexpr int SE = 0, SO = 1;
;   __syncthreads();
;   SLOAD(SE, 0); asm volatile("s_waitcnt vmcnt(0)" ::: "memory"); SWRITE(0, SE); __syncthreads();
;   qkt<NDQ>(pA0, pA1, K_lds, qr, r32, hi); partialSM(pA0, pA1, m_reg, mnA, alA, Cs, thr);
.LBB0_2122:
	s_ashr_i32 s3, s59, 8
	s_lshl_b32 s28, s59, 5
	s_mul_i32 s1, s3, 0x2100
	s_and_b32 s28, s28, 0x1f00
	s_add_i32 s1, s1, s28
	s_add_i32 s28, s1, 0x100
	s_and_b32 s2, s58, 4
	s_and_b32 s0, s59, 7
	s_ashr_i32 s29, s28, 31
	s_mul_i32 s30, s28, 0xc00
	s_mul_hi_i32 s1, s28, 0xc00
	s_add_u32 s30, s5, s30
	s_addc_u32 s1, s35, s1
	s_lshl_b32 s60, s0, 7
	s_lshl_b32 s0, s0, 8
	s_add_u32 s0, s30, s0
	s_addc_u32 s1, s1, 0
	s_mul_i32 s31, s3, 0x18c0000
	s_mul_hi_i32 s30, s3, 0x18c0000
	s_add_u32 s31, s5, s31
	s_addc_u32 s36, s35, s30
	s_lshl_b32 s30, s59, 6
	s_and_b32 s30, s30, 0x100
	v_mov_b32_e32 v58, v190
	s_add_u32 s30, s31, s30
	s_addc_u32 s31, s36, 0
	v_ashrrev_i32_e32 v59, 1, v58
	v_bfe_u32 v188, v58, 5, 1
	v_bfi_b32 v2, s41, v59, v58
	v_mov_b64_e32 v[0:1], s[0:1]
	v_ashrrev_i32_e32 v70, 4, v58
	v_lshl_add_u64 v[48:49], s[30:31], 0, v[180:181]
	v_mad_i64_i32 v[0:1], s[0:1], v2, s40, v[0:1]
	v_lshlrev_b32_e32 v176, 4, v188
	v_add_u32_e32 v16, 32, v70
	v_lshl_add_u64 v[0:1], v[0:1], 0, v[176:177]
	v_mad_i64_i32 v[8:9], s[0:1], v70, s40, v[48:49]
	v_mad_i64_i32 v[12:13], s[0:1], v16, s40, v[48:49]
	global_load_dwordx4 v[124:127], v[0:1], off
	global_load_dwordx4 v[120:123], v[0:1], off offset:32
	global_load_dwordx4 v[116:119], v[0:1], off offset:64
	global_load_dwordx4 v[112:115], v[0:1], off offset:96
	global_load_dwordx4 v[108:111], v[0:1], off offset:128
	global_load_dwordx4 v[104:107], v[0:1], off offset:160
	global_load_dwordx4 v[100:103], v[0:1], off offset:192
	global_load_dwordx4 v[96:99], v[0:1], off offset:224
	s_barrier
	global_load_dwordx4 v[0:3], v[8:9], off offset:2560
	global_load_dwordx4 v[4:7], v[12:13], off offset:2560
	s_nop 0
	global_load_dwordx4 v[8:11], v[8:9], off offset:2048
	s_nop 0
	global_load_dwordx4 v[12:15], v[12:13], off offset:2048
	v_lshlrev_b32_e32 v17, 3, v58
	v_and_b32_e32 v20, 0xfffff0, v70
	v_lshlrev_b32_e32 v21, 1, v70
	v_lshrrev_b32_e32 v22, 1, v70
	v_and_b32_e32 v23, 3, v70
	v_and_b32_e32 v19, 0x78, v17
	v_and_or_b32 v20, v21, 8, v20
	v_and_or_b32 v21, v22, 4, v23
	v_and_b32_e32 v22, 0xfffff0, v16
	v_lshlrev_b32_e32 v23, 1, v16
	v_and_b32_e32 v18, 0x70, v58
	v_bfe_u32 v17, v17, 5, 2
	v_lshlrev_b32_e32 v24, 8, v70
	v_lshlrev_b32_e32 v19, 1, v19
	v_lshlrev_b32_e32 v16, 8, v16
	v_lshrrev_b32_e32 v20, 1, v20
	v_and_or_b32 v22, v23, 8, v22
	v_and_b32_e32 v25, 48, v19
	v_bitop3_b32 v23, v19, v24, v18 bitop3:0xde
	v_bitop3_b32 v16, v19, v16, v18 bitop3:0xde
	v_or_b32_e32 v18, v20, v17
	v_lshrrev_b32_e32 v19, 1, v22
	v_lshlrev_b32_e32 v21, 6, v21
	v_add_u32_e32 v196, 0, v16
	v_lshlrev_b32_e32 v16, 9, v18
	v_or_b32_e32 v17, v19, v17
	v_or3_b32 v16, v16, v21, v25
	v_lshlrev_b32_e32 v17, 9, v17
	v_and_b32_e32 v189, 31, v58
	v_lshlrev_b32_e32 v60, 4, v58
	v_or3_b32 v17, v17, v21, v25
	v_add_u32_e32 v197, 0, v16
	v_add_u32_e32 v195, 0, v23
	v_add_u32_e32 v198, 0, v17
	s_waitcnt vmcnt(0)
	v_lshl_add_u32 v61, v189, 8, 0
	v_and_b32_e32 v62, 0x70, v60
	v_and_b32_e32 v71, 63, v58
	v_and_b32_e32 v63, 0x3fffffc0, v58
	v_lshlrev_b32_e32 v58, 1, v58
	v_and_b32_e32 v182, 0xffffffe0, v59
	v_lshlrev_b32_e32 v59, 3, v71
	v_and_b32_e32 v58, 32, v58
	v_lshl_add_u32 v183, v63, 2, s74
	v_mad_i64_i32 v[66:67], s[0:1], v70, s40, 0
	v_lshl_add_u32 v191, v189, 2, v183
	s_mov_b32 s61, -1
	s_waitcnt vmcnt(3)
	ds_write_b128 v197, v[0:3]
	s_waitcnt vmcnt(2)
	ds_write_b128 v198, v[4:7]
	s_waitcnt vmcnt(1)
	ds_write_b128 v195, v[8:11] offset:32768
	s_waitcnt vmcnt(0)
	ds_write_b128 v196, v[12:15] offset:32768
	v_bitop3_b32 v0, v176, v60, s43 bitop3:0x78
	v_add_u32_e32 v199, v61, v0
	s_waitcnt lgkmcnt(0)
	s_barrier
	ds_read_b128 v[0:3], v199 offset:32768
	ds_read_b128 v[4:7], v199 offset:40960
	s_waitcnt lgkmcnt(1)
	v_mfma_f32_32x32x16_bf16 v[32:47], v[0:3], v[124:127], 0
	v_bitop3_b32 v0, v176, v62, 32 bitop3:0x36
	v_add_u32_e32 v200, v61, v0
	v_and_b32_e32 v60, 0xc0, v60
	v_mov_b32_e32 v192, 0
	s_waitcnt lgkmcnt(0)
	v_mfma_f32_32x32x16_bf16 v[16:31], v[4:7], v[124:127], 0
	ds_read_b128 v[0:3], v200 offset:32768
	ds_read_b128 v[4:7], v200 offset:40960
	s_waitcnt lgkmcnt(1)
	v_mfma_f32_32x32x16_bf16 v[32:47], v[0:3], v[120:123], v[32:47]
	v_bitop3_b32 v0, v176, v62, 64 bitop3:0x36
	v_add_u32_e32 v201, v61, v0
	s_waitcnt lgkmcnt(0)
	v_mfma_f32_32x32x16_bf16 v[16:31], v[4:7], v[120:123], v[16:31]
	ds_read_b128 v[0:3], v201 offset:32768
	ds_read_b128 v[4:7], v201 offset:40960
	s_waitcnt lgkmcnt(1)
	v_mfma_f32_32x32x16_bf16 v[32:47], v[0:3], v[116:119], v[32:47]
	v_bitop3_b32 v0, v176, v62, s44 bitop3:0x36
	v_add_u32_e32 v202, v61, v0
	s_waitcnt lgkmcnt(0)
	v_mfma_f32_32x32x16_bf16 v[16:31], v[4:7], v[116:119], v[16:31]
	ds_read_b128 v[0:3], v202 offset:32768
	ds_read_b128 v[4:7], v202 offset:40960
	s_waitcnt lgkmcnt(1)
	v_mfma_f32_32x32x16_bf16 v[32:47], v[0:3], v[112:115], v[32:47]
	v_bitop3_b32 v0, v176, v62, s45 bitop3:0x36
	v_add_u32_e32 v203, v61, v0
	s_waitcnt lgkmcnt(0)
	v_mfma_f32_32x32x16_bf16 v[16:31], v[4:7], v[112:115], v[16:31]
	ds_read_b128 v[0:3], v203 offset:32768
	ds_read_b128 v[4:7], v203 offset:40960
	s_waitcnt lgkmcnt(1)
	v_mfma_f32_32x32x16_bf16 v[32:47], v[0:3], v[108:111], v[32:47]
	v_bitop3_b32 v0, v176, v62, s46 bitop3:0x36
	v_add_u32_e32 v204, v61, v0
	s_waitcnt lgkmcnt(0)
	v_mfma_f32_32x32x16_bf16 v[16:31], v[4:7], v[108:111], v[16:31]
	ds_read_b128 v[0:3], v204 offset:32768
	ds_read_b128 v[4:7], v204 offset:40960
	s_waitcnt lgkmcnt(1)
	v_mfma_f32_32x32x16_bf16 v[32:47], v[0:3], v[104:107], v[32:47]
	v_bitop3_b32 v0, v176, v62, s42 bitop3:0x36
	v_add_u32_e32 v205, v61, v0
	ds_read_b128 v[50:53], v205 offset:32768
	ds_read_b128 v[54:57], v205 offset:40960
	s_waitcnt lgkmcnt(1)
; #define SLOAD(i, k0) do { sr_[i].vs0 = *reinterpret_cast<const bf16x8*>(vptr + (size_t)((k0) + sr) * vstr); \
;     sr_[i].vs1 = *reinterpret_cast<const bf16x8*>(vptr + (size_t)((k0) + 32 + sr) * vstr); \
;     sr_[i].ks0 = *reinterpret_cast<const bf16x8*>(kptr + (size_t)((k0) + sr) * kstr); \
;     sr_[i].ks1 = *reinterpret_cast<const bf16x8*>(kptr + (size_t)((k0) + 32 + sr) * kstr); } while (0)
; #define SWRITE(b, i) do { *(LAS bf16x8*)(V_lds + (b) * SHM_V + vst0) = sr_[i].vs0;          \
;     *(LAS bf16x8*)(V_lds + (b) * SHM_V + vst1) = sr_[i].vs1; const int kc = sc * 2;               \
;     *(LAS bf16x8*)(K_lds + (b) * SHM_K + KSWZ(sr, kc)) = sr_[i].ks0;                       \
;     *(LAS bf16x8*)(K_lds + (b) * SHM_K + KSWZ(32 + sr, kc)) = sr_[i].ks1; } while (0)
; #define SWAIT() asm volatile("s_waitcnt vmcnt(4)" ::: "memory")
; template <int NDQ, int NDV> ...
;     ...
;   qkt<NDQ>(pA0, pA1, K_lds, qr, r32, hi); partialSM(pA0, pA1, m_reg, mnA, alA, Cs, thr);
;   SLOAD(SO, 64); if (2 < NT) SLOAD(SE, 128);
;   SWAIT(); SWRITE(1, SO); __syncthreads();
	v_mfma_f32_32x32x16_bf16 v[32:47], v[50:53], v[100:103], v[32:47]
	v_bitop3_b32 v50, v176, v62, s47 bitop3:0x36
	v_add_u32_e32 v206, v61, v50
	ds_read_b128 v[50:53], v206 offset:32768
	v_add_u32_e32 v61, 64, v70
	v_mfma_f32_32x32x16_bf16 v[16:31], v[4:7], v[104:107], v[16:31]
	v_mov_b64_e32 v[0:1], s[12:13]
	v_mov_b64_e32 v[14:15], s[26:27]
	v_mov_b64_e32 v[2:3], s[14:15]
	v_mov_b64_e32 v[4:5], s[16:17]
	v_mov_b64_e32 v[6:7], s[18:19]
	v_mov_b64_e32 v[8:9], s[20:21]
	v_mov_b64_e32 v[10:11], s[22:23]
	s_waitcnt lgkmcnt(1)
	v_mfma_f32_32x32x16_bf16 v[16:31], v[54:57], v[100:103], v[16:31]
	ds_read_b128 v[54:57], v206 offset:40960
	v_mov_b64_e32 v[12:13], s[24:25]
	s_waitcnt lgkmcnt(1)
	v_mfma_f32_32x32x16_bf16 v[32:47], v[50:53], v[96:99], v[32:47]
	v_and_or_b32 v50, v59, 24, v60
	v_and_b32_e32 v51, 0x100, v59
	v_or3_b32 v72, v50, v58, v51
	v_mad_i64_i32 v[58:59], s[0:1], v61, s40, v[48:49]
	global_load_dwordx4 v[50:53], v[58:59], off offset:2560
	v_add_u32_e32 v194, 0, v72
	s_waitcnt lgkmcnt(0)
	v_mfma_f32_32x32x16_bf16 v[16:31], v[54:57], v[96:99], v[16:31]
	s_nop 3
	v_max_f32_e32 v54, v33, v33
	v_max_f32_e32 v55, v32, v32
	v_max_f32_e32 v54, v55, v54
	v_max3_f32 v54, v54, v34, v35
	v_max3_f32 v54, v54, v36, v37
	v_max3_f32 v54, v54, v38, v39
	v_max3_f32 v54, v54, v40, v41
	v_max3_f32 v54, v54, v42, v43
	v_max3_f32 v54, v54, v44, v45
	v_max3_f32 v54, v54, v46, v47
	v_max3_f32 v68, v54, v16, v17
	v_max3_f32 v68, v68, v18, v19
	v_max3_f32 v68, v68, v20, v21
	v_max3_f32 v68, v68, v22, v23
	v_max3_f32 v68, v68, v24, v25
	v_max3_f32 v68, v68, v26, v27
	v_add_u32_e32 v54, 0x60, v70
	v_max3_f32 v73, v68, v28, v29
	v_add_u32_e32 v68, 0xa0, v70
	v_mad_i64_i32 v[62:63], s[0:1], v54, s40, v[48:49]
	v_mad_i64_i32 v[68:69], s[0:1], v68, s40, v[48:49]
	v_add_u32_e32 v70, 0x80, v70
	global_load_dwordx4 v[54:57], v[62:63], off offset:2560
	s_nop 0
	global_load_dwordx4 v[58:61], v[58:59], off offset:2048
	s_nop 0
	global_load_dwordx4 v[62:65], v[62:63], off offset:2048
	v_mad_i64_i32 v[48:49], s[0:1], v70, s40, v[48:49]
	global_load_dwordx4 v[132:135], v[68:69], off offset:2048
	global_load_dwordx4 v[136:139], v[68:69], off offset:2560
	global_load_dwordx4 v[140:143], v[48:49], off offset:2048
	global_load_dwordx4 v[128:131], v[48:49], off offset:2560
	v_max3_f32 v48, v73, v30, v31
	v_mov_b32_e32 v49, v48
	s_nop 1
	v_permlane32_swap_b32_e32 v48, v49
	v_max_f32_e32 v49, v49, v49
	v_max_f32_e32 v48, v48, v48
	v_max_f32_e32 v48, v48, v49
	v_add_f32_e32 v49, 0x7149f2ca, v48
	v_max_f32_e32 v48, 0xf149f2ca, v48
	v_cmp_ge_f32_e32 vcc, s48, v49
	v_sub_f32_e32 v49, 0xf149f2ca, v48
	v_mul_f32_e32 v49, 0x3e0293ee, v49
	v_exp_f32_e32 v49, v49
	s_cmp_eq_u64 vcc, exec
	s_cselect_b64 vcc, -1, 0
	v_cndmask_b32_e32 v160, v48, v186, vcc
	v_mul_f32_e32 v48, 0xbe0293ee, v160
	v_cndmask_b32_e64 v207, v49, 1.0, vcc
	v_mov_b32_e32 v49, v48
	v_fmamk_f32 v32, v32, 0x3e0293ee, v48
	v_fmamk_f32 v33, v33, 0x3e0293ee, v48
	v_fmamk_f32 v34, v34, 0x3e0293ee, v48
	v_fmamk_f32 v35, v35, 0x3e0293ee, v48
	v_fmamk_f32 v36, v36, 0x3e0293ee, v48
	v_fmamk_f32 v37, v37, 0x3e0293ee, v48
	v_fmamk_f32 v38, v38, 0x3e0293ee, v48
	v_fmamk_f32 v39, v39, 0x3e0293ee, v48
	v_fmamk_f32 v40, v40, 0x3e0293ee, v48
	v_fmamk_f32 v41, v41, 0x3e0293ee, v48
	v_fmamk_f32 v42, v42, 0x3e0293ee, v48
	v_fmamk_f32 v43, v43, 0x3e0293ee, v48
	v_fmamk_f32 v44, v44, 0x3e0293ee, v48
	v_fmamk_f32 v45, v45, 0x3e0293ee, v48
	v_fmamk_f32 v46, v46, 0x3e0293ee, v48
	v_fmac_f32_e32 v49, 0x3e0293ee, v47
	v_pk_fma_f32 v[154:155], v[16:17], s[4:5], v[48:49] op_sel_hi:[1,0,0]
	v_exp_f32_e32 v175, v32
	v_exp_f32_e32 v214, v33
	v_exp_f32_e32 v173, v34
	v_exp_f32_e32 v211, v35
	v_exp_f32_e32 v172, v36
	v_exp_f32_e32 v174, v37
	v_exp_f32_e32 v170, v38
	v_exp_f32_e32 v171, v39
	v_exp_f32_e32 v167, v40
	v_exp_f32_e32 v169, v41
	v_exp_f32_e32 v166, v42
	v_exp_f32_e32 v168, v43
	v_exp_f32_e32 v163, v44
	v_exp_f32_e32 v165, v45
	v_exp_f32_e32 v162, v46
	v_exp_f32_e32 v164, v49
	v_mad_i64_i32 v[16:17], s[30:31], s3, v187, v[66:67]
	s_waitcnt vmcnt(4)
	v_lshl_or_b32 v16, s2, 6, v16
	v_pk_fma_f32 v[150:151], v[30:31], s[4:5], v[48:49] op_sel_hi:[1,0,0]
	v_pk_fma_f32 v[156:157], v[28:29], s[4:5], v[48:49] op_sel_hi:[1,0,0]
	v_pk_fma_f32 v[158:159], v[26:27], s[4:5], v[48:49] op_sel_hi:[1,0,0]
	v_pk_fma_f32 v[144:145], v[24:25], s[4:5], v[48:49] op_sel_hi:[1,0,0]
	v_pk_fma_f32 v[146:147], v[22:23], s[4:5], v[48:49] op_sel_hi:[1,0,0]
	v_pk_fma_f32 v[148:149], v[20:21], s[4:5], v[48:49] op_sel_hi:[1,0,0]
	v_pk_fma_f32 v[152:153], v[18:19], s[4:5], v[48:49] op_sel_hi:[1,0,0]
	s_waitcnt vmcnt(7)
	ds_write_b128 v197, v[50:53] offset:16384
	s_waitcnt vmcnt(6)
	ds_write_b128 v198, v[54:57] offset:16384
	s_waitcnt vmcnt(5)
	ds_write_b128 v195, v[58:61] offset:49152
	s_waitcnt vmcnt(4)
	ds_write_b128 v196, v[62:65] offset:49152
	v_lshl_add_u64 v[184:185], v[178:179], 0, v[16:17]
	v_mov_b64_e32 v[62:63], v[14:15]
	v_mov_b64_e32 v[46:47], v[14:15]
	v_mov_b64_e32 v[30:31], v[14:15]
	v_cmp_gt_u32_e64 s[0:1], 32, v71
	v_add_u32_e32 v193, s75, v72
	v_mov_b64_e32 v[60:61], v[12:13]
	v_mov_b64_e32 v[58:59], v[10:11]
	v_mov_b64_e32 v[56:57], v[8:9]
	v_mov_b64_e32 v[54:55], v[6:7]
	v_mov_b64_e32 v[52:53], v[4:5]
	v_mov_b64_e32 v[50:51], v[2:3]
	v_mov_b64_e32 v[48:49], v[0:1]
	v_mov_b64_e32 v[44:45], v[12:13]
	v_mov_b64_e32 v[42:43], v[10:11]
	v_mov_b64_e32 v[40:41], v[8:9]
	v_mov_b64_e32 v[38:39], v[6:7]
	v_mov_b64_e32 v[36:37], v[4:5]
	v_mov_b64_e32 v[34:35], v[2:3]
	v_mov_b64_e32 v[32:33], v[0:1]
	v_mov_b64_e32 v[28:29], v[12:13]
	v_mov_b64_e32 v[26:27], v[10:11]
	v_mov_b64_e32 v[24:25], v[8:9]
	v_mov_b64_e32 v[22:23], v[6:7]
	v_mov_b64_e32 v[20:21], v[4:5]
	v_mov_b64_e32 v[18:19], v[2:3]
	v_mov_b64_e32 v[16:17], v[0:1]
	v_mov_b32_e32 v236, v175
	v_mov_b32_e32 v237, v214
	v_mov_b32_e32 v238, v173
	v_mov_b32_e32 v239, v211
	v_mov_b32_e32 v240, v172
	v_mov_b32_e32 v241, v174
	v_mov_b32_e32 v242, v170
	v_mov_b32_e32 v243, v171
	v_mov_b32_e32 v244, v167
	v_mov_b32_e32 v245, v169
	v_mov_b32_e32 v246, v166
	v_mov_b32_e32 v247, v168
	v_mov_b32_e32 v248, v163
	v_mov_b32_e32 v249, v165
	v_mov_b32_e32 v250, v162
	v_mov_b32_e32 v251, v164
	s_waitcnt lgkmcnt(0)
	s_barrier
; #define SBAR() __builtin_amdgcn_sched_barrier(0)
; #define SLOAD(i, k0) do { sr_[i].vs0 = *reinterpret_cast<const bf16x8*>(vptr + (size_t)((k0) + sr) * vstr); \
;     sr_[i].vs1 = *reinterpret_cast<const bf16x8*>(vptr + (size_t)((k0) + 32 + sr) * vstr); \
;     sr_[i].ks0 = *reinterpret_cast<const bf16x8*>(kptr + (size_t)((k0) + sr) * kstr); \
;     sr_[i].ks1 = *reinterpret_cast<const bf16x8*>(kptr + (size_t)((k0) + 32 + sr) * kstr); } while (0)
; template <int D0> __device__ __forceinline__ void pv_one(f32x16& od, int vb, bf16x8 pa0, bf16x8 pa1, bf16x8 pa2, bf16x8 pa3) {
;   const s16x4 l0 = tr_read<v_rd_off(D0, 0, 0)>(vb), h0 = tr_read<v_rd_off(D0, 0, 1)>(vb), l1 = tr_read<v_rd_off(D0, 1, 0)>(vb), h1 = tr_read<v_rd_off(D0, 1, 1)>(vb);
;   const s16x4 l2 = tr_read<v_rd_off(D0, 2, 0)>(vb), h2 = tr_read<v_rd_off(D0, 2, 1)>(vb), l3 = tr_read<v_rd_off(D0, 3, 0)>(vb), h3 = tr_read<v_rd_off(D0, 3, 1)>(vb);
;   asm volatile("s_waitcnt lgkmcnt(0)" ::: "memory"); SBAR();
;     ...
;   od = __builtin_amdgcn_mfma_f32_32x32x16_bf16(pa0, PK(l0, h0), od, 0, 0, 0);
;   od = __builtin_amdgcn_mfma_f32_32x32x16_bf16(pa1, PK(l1, h1), od, 0, 0, 0);
;   od = __builtin_amdgcn_mfma_f32_32x32x16_bf16(pa2, PK(l2, h2), od, 0, 0, 0);
;   od = __builtin_amdgcn_mfma_f32_32x32x16_bf16(pa3, PK(l3, h3), od, 0, 0, 0);
;     ...
; }
; template <int NDV>
; __device__ __forceinline__ void pv_d0(f32x16* o, int vb, bf16x8 pa0, bf16x8 pa1, bf16x8 pa2, bf16x8 pa3) {
;   pv_one<0>(o[0], vb, pa0, pa1, pa2, pa3); pv_one<1>(o[1], vb, pa0, pa1, pa2, pa3);
;   if constexpr (NDV == 4) { pv_one<2>(o[2], vb, pa0, pa1, pa2, pa3); pv_one<3>(o[3], vb, pa0, pa1, pa2, pa3); }
; }
; template <int NDQ, int NDV> ...
;     ...
;     SBAR(); qkt<NDQ>(pB0, pB1, K_lds + SHM_K, qr, r32, hi);
;     finishSM(pA0, pA1, alA, l_reg, pa0, pa1, pa2, pa3); SBAR();
;     SLOAD(SO, (j + 2) * 64); SBAR();
;     pv_d0<NDV>(o, vb0, pa0, pa1, pa2, pa3); partialSM(pB0, pB1, m_reg, mnB, alB, Cs, thr);
.LBB0_2123:
	ds_read_b128 v[64:67], v199 offset:49152
	ds_read_b128 v[68:71], v199 offset:57344
	ds_read_b128 v[216:219], v200 offset:49152
	ds_read_b128 v[220:223], v200 offset:57344
	v_add_f32_e32 v161, 0, v236
	v_add_f32_e32 v161, v237, v161
	s_waitcnt lgkmcnt(3)
	v_mfma_f32_32x32x16_bf16 v[80:95], v[64:67], v[124:127], 0
	v_add_f32_e32 v161, v238, v161
	v_add_f32_e32 v161, v239, v161
	v_add_f32_e32 v161, v240, v161
	v_add_f32_e32 v161, v241, v161
	v_add_f32_e32 v161, v242, v161
	v_add_f32_e32 v161, v243, v161
	s_waitcnt lgkmcnt(2)
	v_mfma_f32_32x32x16_bf16 v[64:79], v[68:71], v[124:127], 0
	v_add_f32_e32 v161, v244, v161
	v_add_f32_e32 v161, v245, v161
	v_add_f32_e32 v161, v246, v161
	v_add_f32_e32 v161, v247, v161
	v_exp_f32_e32 v154, v154
	s_waitcnt lgkmcnt(1)
	v_mfma_f32_32x32x16_bf16 v[80:95], v[216:219], v[120:123], v[80:95]
	v_add_f32_e32 v161, v248, v161
	v_exp_f32_e32 v155, v155
	v_add_f32_e32 v161, v249, v161
	v_exp_f32_e32 v152, v152
	s_waitcnt lgkmcnt(0)
	v_mfma_f32_32x32x16_bf16 v[64:79], v[220:223], v[120:123], v[64:79]
	ds_read_b128 v[216:219], v201 offset:49152
	ds_read_b128 v[220:223], v201 offset:57344
	v_add_f32_e32 v161, v250, v161
	v_exp_f32_e32 v153, v153
	v_add_f32_e32 v161, v251, v161
	v_exp_f32_e32 v148, v148
	s_waitcnt lgkmcnt(1)
	v_mfma_f32_32x32x16_bf16 v[80:95], v[216:219], v[116:119], v[80:95]
	v_add_f32_e32 v161, v154, v161
	v_exp_f32_e32 v149, v149
	v_add_f32_e32 v161, v155, v161
	v_exp_f32_e32 v146, v146
	s_waitcnt lgkmcnt(0)
	v_mfma_f32_32x32x16_bf16 v[64:79], v[220:223], v[116:119], v[64:79]
	ds_read_b128 v[216:219], v202 offset:49152
	ds_read_b128 v[220:223], v202 offset:57344
	v_add_f32_e32 v161, v152, v161
	v_exp_f32_e32 v147, v147
	v_add_f32_e32 v161, v153, v161
	v_exp_f32_e32 v144, v144
	s_waitcnt lgkmcnt(1)
	v_mfma_f32_32x32x16_bf16 v[80:95], v[216:219], v[112:115], v[80:95]
	v_add_f32_e32 v161, v148, v161
	v_exp_f32_e32 v145, v145
	v_add_f32_e32 v161, v149, v161
	v_exp_f32_e32 v158, v158
	s_waitcnt lgkmcnt(0)
	v_mfma_f32_32x32x16_bf16 v[64:79], v[220:223], v[112:115], v[64:79]
	ds_read_b128 v[216:219], v203 offset:49152
	ds_read_b128 v[220:223], v203 offset:57344
	v_add_f32_e32 v161, v146, v161
	v_exp_f32_e32 v159, v159
	v_add_f32_e32 v161, v147, v161
	v_exp_f32_e32 v156, v156
	s_waitcnt lgkmcnt(1)
	v_mfma_f32_32x32x16_bf16 v[80:95], v[216:219], v[108:111], v[80:95]
	v_add_f32_e32 v161, v144, v161
	v_exp_f32_e32 v157, v157
	v_add_f32_e32 v161, v145, v161
	v_exp_f32_e32 v150, v150
	s_waitcnt lgkmcnt(0)
	v_mfma_f32_32x32x16_bf16 v[64:79], v[220:223], v[108:111], v[64:79]
	ds_read_b128 v[216:219], v204 offset:49152
	ds_read_b128 v[220:223], v204 offset:57344
	v_add_f32_e32 v161, v158, v161
	v_exp_f32_e32 v151, v151
	v_add_f32_e32 v161, v159, v161
	v_add_f32_e32 v161, v156, v161
	v_add_f32_e32 v161, v157, v161
	s_waitcnt lgkmcnt(1)
	v_mfma_f32_32x32x16_bf16 v[80:95], v[216:219], v[104:107], v[80:95]
	v_add_f32_e32 v161, v150, v161
	v_add_f32_e32 v208, v151, v161
	v_mov_b32_e32 v209, v208
	v_cvt_pk_bf16_f32 v210, v236, v237
	v_cvt_pk_bf16_f32 v211, v238, v239
	v_cvt_pk_bf16_f32 v212, v240, v241
	s_waitcnt lgkmcnt(0)
	v_mfma_f32_32x32x16_bf16 v[64:79], v[220:223], v[104:107], v[64:79]
	ds_read_b128 v[216:219], v205 offset:49152
	ds_read_b128 v[220:223], v205 offset:57344
	v_permlane32_swap_b32_e32 v208, v209
	v_cvt_pk_bf16_f32 v213, v242, v243
	v_cvt_pk_bf16_f32 v170, v244, v245
	v_cvt_pk_bf16_f32 v171, v246, v247
	v_permlane32_swap_b32_e32 v210, v212
	v_cvt_pk_bf16_f32 v172, v248, v249
	s_waitcnt lgkmcnt(1)
	v_mfma_f32_32x32x16_bf16 v[80:95], v[216:219], v[100:103], v[80:95]
	v_cvt_pk_bf16_f32 v173, v250, v251
	v_cvt_pk_bf16_f32 v162, v154, v155
	v_cvt_pk_bf16_f32 v163, v152, v153
	v_cvt_pk_bf16_f32 v164, v148, v149
	v_cvt_pk_bf16_f32 v165, v146, v147
	v_cvt_pk_bf16_f32 v166, v144, v145
	s_waitcnt lgkmcnt(0)
	v_mfma_f32_32x32x16_bf16 v[64:79], v[220:223], v[100:103], v[64:79]
	ds_read_b128 v[216:219], v206 offset:49152
	ds_read_b128 v[220:223], v206 offset:57344
	v_cvt_pk_bf16_f32 v167, v158, v159
	v_cvt_pk_bf16_f32 v168, v156, v157
	v_cvt_pk_bf16_f32 v169, v150, v151
	v_permlane32_swap_b32_e32 v211, v213
	v_permlane32_swap_b32_e32 v170, v172
	v_permlane32_swap_b32_e32 v171, v173
	s_waitcnt lgkmcnt(1)
	v_mfma_f32_32x32x16_bf16 v[80:95], v[216:219], v[96:99], v[80:95]
	v_permlane32_swap_b32_e32 v162, v164
	v_permlane32_swap_b32_e32 v163, v165
	v_permlane32_swap_b32_e32 v166, v168
	v_permlane32_swap_b32_e32 v167, v169
	s_waitcnt lgkmcnt(0)
	v_mfma_f32_32x32x16_bf16 v[64:79], v[220:223], v[96:99], v[64:79]
	v_add_co_u32_e32 v148, vcc, s50, v184
	s_nop 1
	v_addc_co_u32_e32 v149, vcc, -1, v185, vcc
	v_add_co_u32_e32 v152, vcc, s51, v184
	s_nop 1
	v_addc_co_u32_e32 v153, vcc, -1, v185, vcc
	global_load_dwordx4 v[144:147], v[148:149], off
	s_nop 0
	global_load_dwordx4 v[148:151], v[148:149], off offset:-512
	s_nop 0
	global_load_dwordx4 v[156:159], v[152:153], off
	s_nop 0
	global_load_dwordx4 v[152:155], v[152:153], off offset:-512
	ds_read_b64_tr_b16 v[214:215], v194 offset:0
	ds_read_b64_tr_b16 v[216:217], v194 offset:0x800
	ds_read_b64_tr_b16 v[218:219], v194 offset:0x1000
	ds_read_b64_tr_b16 v[220:221], v194 offset:0x1800
	ds_read_b64_tr_b16 v[222:223], v194 offset:0x2000
	ds_read_b64_tr_b16 v[224:225], v194 offset:0x2800
	ds_read_b64_tr_b16 v[226:227], v194 offset:0x3000
	ds_read_b64_tr_b16 v[228:229], v194 offset:0x3800
	s_waitcnt lgkmcnt(6)
	v_mfma_f32_32x32x16_bf16 v[0:15], v[210:213], v[214:217], v[0:15]
	ds_read_b64_tr_b16 v[214:215], v194 offset:0x200
	ds_read_b64_tr_b16 v[216:217], v194 offset:0xa00
	v_max_f32_e32 v161, v81, v81
	v_max_f32_e32 v174, v80, v80
	v_max_f32_e32 v161, v174, v161
	v_max3_f32 v161, v161, v82, v83
	v_max3_f32 v161, v161, v84, v85
	v_max3_f32 v161, v161, v86, v87
	s_waitcnt lgkmcnt(6)
; #define SWRITE(b, i) do { *(LAS bf16x8*)(V_lds + (b) * SHM_V + vst0) = sr_[i].vs0;          \
;     *(LAS bf16x8*)(V_lds + (b) * SHM_V + vst1) = sr_[i].vs1; const int kc = sc * 2;               \
;     *(LAS bf16x8*)(K_lds + (b) * SHM_K + KSWZ(sr, kc)) = sr_[i].ks0;                       \
;     *(LAS bf16x8*)(K_lds + (b) * SHM_K + KSWZ(32 + sr, kc)) = sr_[i].ks1; } while (0)
; #define SWAIT() asm volatile("s_waitcnt vmcnt(4)" ::: "memory")
; #define RESC(a) do { if (__any((a) < 1.f)) { if (hi == 0) al_l[r32] = (a); asm volatile("s_waitcnt lgkmcnt(0)" ::: "memory"); \
;     _Pragma("unroll") for (int d = 0; d < NDV; ++d) _Pragma("unroll") for (int r = 0; r < 16; ++r) o[d][r] *= al_l[crow(r, hi)]; } } while (0)
; __device__ __forceinline__ void partialSM(f32x16& p0, f32x16& p1, float& m_reg, float& mn, float& alpha, float C, float thr) {
;   float pmax = p0[0];
; #pragma unroll
;   for (int r = 1; r < 16; ++r) pmax = fmaxf(pmax, p0[r]);
; #pragma unroll
;   for (int r = 0; r < 16; ++r) pmax = fmaxf(pmax, p1[r]);
;   { auto rr = __builtin_amdgcn_permlane32_swap(__float_as_uint(pmax), __float_as_uint(pmax), false, false);
;     pmax = fmaxf(__uint_as_float(rr[0]), __uint_as_float(rr[1])); }
;   if (__builtin_expect(__all(pmax - m_reg <= thr), 1)) { mn = m_reg; alpha = 1.f; }
;   else { mn = fmaxf(m_reg, pmax); alpha = __builtin_amdgcn_exp2f((m_reg - mn) * C); m_reg = mn; }
;   const float mnC = -mn * C;
; #pragma unroll
;   for (int r = 0; r < 16; ++r) p0[r] = fmaf(p0[r], C, mnC);
; #pragma unroll
;   for (int r = 0; r < 16; ++r) p1[r] = fmaf(p1[r], C, mnC);
; #pragma unroll
;   for (int r = 0; r < 16; ++r) p0[r] = __builtin_amdgcn_exp2f(p0[r]);
; template <int NDQ, int NDV> ...
;     ...
;     pv_d0<NDV>(o, vb0, pa0, pa1, pa2, pa3); partialSM(pB0, pB1, m_reg, mnB, alB, Cs, thr);
;     __syncthreads(); SWAIT(); SWRITE(0, SE);
;     RESC(alB); __syncthreads();
	v_mfma_f32_32x32x16_bf16 v[0:15], v[170:173], v[218:221], v[0:15]
	ds_read_b64_tr_b16 v[218:219], v194 offset:0x1200
	ds_read_b64_tr_b16 v[220:221], v194 offset:0x1a00
	v_max3_f32 v161, v161, v88, v89
	v_max3_f32 v161, v161, v90, v91
	v_max3_f32 v161, v161, v92, v93
	v_max3_f32 v161, v161, v94, v95
	v_max3_f32 v161, v161, v64, v65
	v_max3_f32 v161, v161, v66, v67
	s_waitcnt lgkmcnt(6)
	v_mfma_f32_32x32x16_bf16 v[0:15], v[162:165], v[222:225], v[0:15]
	ds_read_b64_tr_b16 v[222:223], v194 offset:0x2200
	ds_read_b64_tr_b16 v[224:225], v194 offset:0x2a00
	ds_read_b64_tr_b16 v[230:231], v194 offset:0x3200
	ds_read_b64_tr_b16 v[232:233], v194 offset:0x3a00
	v_max3_f32 v161, v161, v68, v69
	v_max3_f32 v161, v161, v70, v71
	v_max3_f32 v161, v161, v72, v73
	v_max3_f32 v161, v161, v74, v75
	v_max3_f32 v161, v161, v76, v77
	v_max3_f32 v161, v161, v78, v79
	s_waitcnt lgkmcnt(8)
	v_mfma_f32_32x32x16_bf16 v[0:15], v[166:169], v[226:229], v[0:15]
	v_mov_b32_e32 v174, v161
	s_nop 1
	v_permlane32_swap_b32_e32 v161, v174
	v_max_f32_e32 v175, v174, v174
	v_max_f32_e32 v161, v161, v161
	v_max_f32_e32 v161, v161, v175
	s_waitcnt lgkmcnt(6)
	v_mfma_f32_32x32x16_bf16 v[48:63], v[210:213], v[214:217], v[48:63]
	ds_read_b64_tr_b16 v[214:215], v194 offset:0x400
	ds_read_b64_tr_b16 v[216:217], v194 offset:0xc00
	v_max_f32_e32 v235, v160, v160
	v_sub_f32_e32 v175, v161, v160
	v_max_f32_e32 v161, v235, v161
	v_sub_f32_e32 v235, v160, v161
	v_mul_f32_e32 v235, 0x3e0293ee, v235
	s_waitcnt lgkmcnt(6)
	v_mfma_f32_32x32x16_bf16 v[48:63], v[170:173], v[218:221], v[48:63]
	ds_read_b64_tr_b16 v[218:219], v194 offset:0x1400
	ds_read_b64_tr_b16 v[220:221], v194 offset:0x1c00
	v_exp_f32_e32 v235, v235
	v_cmp_ge_f32_e32 vcc, s48, v175
	s_cmp_eq_u64 vcc, exec
	s_cselect_b64 s[2:3], -1, 0
	v_cndmask_b32_e64 v234, v161, v160, s[2:3]
	s_waitcnt lgkmcnt(6)
	v_mfma_f32_32x32x16_bf16 v[48:63], v[162:165], v[222:225], v[48:63]
	ds_read_b64_tr_b16 v[222:223], v194 offset:0x2400
	ds_read_b64_tr_b16 v[224:225], v194 offset:0x2c00
	ds_read_b64_tr_b16 v[226:227], v194 offset:0x3400
	ds_read_b64_tr_b16 v[228:229], v194 offset:0x3c00
	v_mul_f32_e32 v175, 0xbe0293ee, v234
	v_fmamk_f32 v80, v80, 0x3e0293ee, v175
	v_fmamk_f32 v81, v81, 0x3e0293ee, v175
	v_fmamk_f32 v82, v82, 0x3e0293ee, v175
	v_fmamk_f32 v83, v83, 0x3e0293ee, v175
	v_fmamk_f32 v84, v84, 0x3e0293ee, v175
	s_waitcnt lgkmcnt(8)
	v_mfma_f32_32x32x16_bf16 v[48:63], v[166:169], v[230:233], v[48:63]
	v_fmamk_f32 v85, v85, 0x3e0293ee, v175
	v_fmamk_f32 v86, v86, 0x3e0293ee, v175
	v_fmamk_f32 v87, v87, 0x3e0293ee, v175
	v_fmamk_f32 v88, v88, 0x3e0293ee, v175
	v_fmamk_f32 v89, v89, 0x3e0293ee, v175
	v_fmamk_f32 v90, v90, 0x3e0293ee, v175
	s_waitcnt lgkmcnt(6)
	v_mfma_f32_32x32x16_bf16 v[32:47], v[210:213], v[214:217], v[32:47]
	ds_read_b64_tr_b16 v[214:215], v194 offset:0x600
	ds_read_b64_tr_b16 v[216:217], v194 offset:0xe00
	v_fmamk_f32 v91, v91, 0x3e0293ee, v175
	v_fmamk_f32 v92, v92, 0x3e0293ee, v175
	v_fmamk_f32 v93, v93, 0x3e0293ee, v175
	v_fmamk_f32 v94, v94, 0x3e0293ee, v175
	v_fmamk_f32 v95, v95, 0x3e0293ee, v175
	s_waitcnt lgkmcnt(6)
	v_mfma_f32_32x32x16_bf16 v[32:47], v[170:173], v[218:221], v[32:47]
	ds_read_b64_tr_b16 v[218:219], v194 offset:0x1600
	ds_read_b64_tr_b16 v[220:221], v194 offset:0x1e00
	v_exp_f32_e32 v236, v80
	v_exp_f32_e32 v237, v81
	v_exp_f32_e32 v238, v82
	s_waitcnt lgkmcnt(6)
	v_mfma_f32_32x32x16_bf16 v[32:47], v[162:165], v[222:225], v[32:47]
	ds_read_b64_tr_b16 v[222:223], v194 offset:0x2600
	ds_read_b64_tr_b16 v[224:225], v194 offset:0x2e00
	ds_read_b64_tr_b16 v[230:231], v194 offset:0x3600
	ds_read_b64_tr_b16 v[232:233], v194 offset:0x3e00
	v_exp_f32_e32 v239, v83
	v_exp_f32_e32 v240, v84
	v_exp_f32_e32 v241, v85
	s_waitcnt lgkmcnt(8)
	v_mfma_f32_32x32x16_bf16 v[32:47], v[166:169], v[226:229], v[32:47]
	v_exp_f32_e32 v242, v86
	v_exp_f32_e32 v243, v87
	v_exp_f32_e32 v244, v88
	s_waitcnt lgkmcnt(6)
	v_mfma_f32_32x32x16_bf16 v[16:31], v[210:213], v[214:217], v[16:31]
	v_exp_f32_e32 v245, v89
	v_exp_f32_e32 v246, v90
	v_exp_f32_e32 v247, v91
	s_waitcnt lgkmcnt(4)
	v_mfma_f32_32x32x16_bf16 v[16:31], v[170:173], v[218:221], v[16:31]
	v_exp_f32_e32 v248, v92
	v_exp_f32_e32 v249, v93
	v_exp_f32_e32 v250, v94
	s_waitcnt lgkmcnt(2)
	v_mfma_f32_32x32x16_bf16 v[16:31], v[162:165], v[222:225], v[16:31]
	v_exp_f32_e32 v251, v95
	s_waitcnt lgkmcnt(0)
	v_mfma_f32_32x32x16_bf16 v[16:31], v[166:169], v[230:233], v[16:31]
	s_barrier
	s_waitcnt vmcnt(4)
	v_cndmask_b32_e64 v210, v235, 1.0, s[2:3]
	v_cmp_gt_f32_e32 vcc, 1.0, v210
	s_waitcnt vmcnt(4)
	ds_write_b128 v197, v[128:131]
	ds_write_b128 v198, v[136:139]
	ds_write_b128 v195, v[140:143] offset:32768
	ds_write_b128 v196, v[132:135] offset:32768
	s_cbranch_vccz .LBB0_2127
	s_and_saveexec_b64 s[30:31], s[0:1]
	ds_write_b32 v191, v210 offset:128
	s_or_b64 exec, exec, s[30:31]
	s_waitcnt lgkmcnt(0)
	v_add_u32_e32 v174, v183, v176
	ds_read_b128 v[162:165], v174 offset:224
	ds_read_b128 v[166:169], v174 offset:192
	ds_read_b128 v[170:173], v174 offset:160
	ds_read_b128 v[212:215], v174 offset:128
	s_waitcnt lgkmcnt(3)
	v_pk_mul_f32 v[12:13], v[12:13], v[162:163]
	s_waitcnt lgkmcnt(2)
	v_pk_mul_f32 v[8:9], v[8:9], v[166:167]
	s_waitcnt lgkmcnt(1)
	v_pk_mul_f32 v[4:5], v[4:5], v[170:171]
	v_pk_mul_f32 v[14:15], v[14:15], v[164:165]
	v_pk_mul_f32 v[10:11], v[10:11], v[168:169]
	v_pk_mul_f32 v[6:7], v[6:7], v[172:173]
	s_waitcnt lgkmcnt(0)
	v_pk_mul_f32 v[2:3], v[2:3], v[214:215]
	v_pk_mul_f32 v[0:1], v[0:1], v[212:213]
	v_pk_mul_f32 v[60:61], v[60:61], v[162:163]
	v_pk_mul_f32 v[56:57], v[56:57], v[166:167]
	v_pk_mul_f32 v[52:53], v[52:53], v[170:171]
	v_pk_mul_f32 v[62:63], v[62:63], v[164:165]
	v_pk_mul_f32 v[58:59], v[58:59], v[168:169]
	v_pk_mul_f32 v[54:55], v[54:55], v[172:173]
	v_pk_mul_f32 v[50:51], v[50:51], v[214:215]
	v_pk_mul_f32 v[48:49], v[48:49], v[212:213]
	v_pk_mul_f32 v[44:45], v[44:45], v[162:163]
	v_pk_mul_f32 v[40:41], v[40:41], v[166:167]
	v_pk_mul_f32 v[36:37], v[36:37], v[170:171]
	v_pk_mul_f32 v[46:47], v[46:47], v[164:165]
	v_pk_mul_f32 v[42:43], v[42:43], v[168:169]
	v_pk_mul_f32 v[38:39], v[38:39], v[172:173]
	v_pk_mul_f32 v[34:35], v[34:35], v[214:215]
	v_pk_mul_f32 v[32:33], v[32:33], v[212:213]
	v_pk_mul_f32 v[28:29], v[28:29], v[162:163]
	v_pk_mul_f32 v[24:25], v[24:25], v[166:167]
	v_pk_mul_f32 v[20:21], v[20:21], v[170:171]
	v_pk_mul_f32 v[30:31], v[30:31], v[164:165]
	v_pk_mul_f32 v[26:27], v[26:27], v[168:169]
	v_pk_mul_f32 v[22:23], v[22:23], v[172:173]
	v_pk_mul_f32 v[18:19], v[18:19], v[214:215]
	v_pk_mul_f32 v[16:17], v[16:17], v[212:213]
; #define SBAR() __builtin_amdgcn_sched_barrier(0)
; #define SLOAD(i, k0) do { sr_[i].vs0 = *reinterpret_cast<const bf16x8*>(vptr + (size_t)((k0) + sr) * vstr); \
;     sr_[i].vs1 = *reinterpret_cast<const bf16x8*>(vptr + (size_t)((k0) + 32 + sr) * vstr); \
;     sr_[i].ks0 = *reinterpret_cast<const bf16x8*>(kptr + (size_t)((k0) + sr) * kstr); \
;     sr_[i].ks1 = *reinterpret_cast<const bf16x8*>(kptr + (size_t)((k0) + 32 + sr) * kstr); } while (0)
; __device__ __forceinline__ void partialSM(f32x16& p0, f32x16& p1, float& m_reg, float& mn, float& alpha, float C, float thr) {
;     ...
;   else { mn = fmaxf(m_reg, pmax); alpha = __builtin_amdgcn_exp2f((m_reg - mn) * C); m_reg = mn; }
;   const float mnC = -mn * C;
; #pragma unroll
;   for (int r = 0; r < 16; ++r) p0[r] = fmaf(p0[r], C, mnC);
; #pragma unroll
;   for (int r = 0; r < 16; ++r) p1[r] = fmaf(p1[r], C, mnC);
; #pragma unroll
;   for (int r = 0; r < 16; ++r) p0[r] = __builtin_amdgcn_exp2f(p0[r]);
; }
; template <int NDQ, int NDV> ...
;     ...
;     SBAR(); qkt<NDQ>(pA0, pA1, K_lds, qr, r32, hi);
;     finishSM(pB0, pB1, alB, l_reg, pa0, pa1, pa2, pa3); SBAR();
;     if (j + 3 < NT) SLOAD(SE, (j + 3) * 64); SBAR();
.LBB0_2127:
	v_mov_b32_e32 v211, v234
	v_fmamk_f32 v221, v64, 0x3e0293ee, v175
	v_fmamk_f32 v222, v65, 0x3e0293ee, v175
	v_fmamk_f32 v223, v66, 0x3e0293ee, v175
	v_fmamk_f32 v224, v67, 0x3e0293ee, v175
	v_fmamk_f32 v225, v68, 0x3e0293ee, v175
	v_fmamk_f32 v214, v69, 0x3e0293ee, v175
	v_fmamk_f32 v215, v70, 0x3e0293ee, v175
	v_fmamk_f32 v216, v71, 0x3e0293ee, v175
	v_fmamk_f32 v217, v72, 0x3e0293ee, v175
	v_fmamk_f32 v218, v73, 0x3e0293ee, v175
	v_fmamk_f32 v219, v74, 0x3e0293ee, v175
	v_fmamk_f32 v220, v75, 0x3e0293ee, v175
	v_fmamk_f32 v213, v76, 0x3e0293ee, v175
	v_fmamk_f32 v226, v77, 0x3e0293ee, v175
	v_fmamk_f32 v227, v78, 0x3e0293ee, v175
	v_fmamk_f32 v212, v79, 0x3e0293ee, v175
	s_add_i32 s61, s61, 2
	s_waitcnt lgkmcnt(0)
	s_barrier
	ds_read_b128 v[64:67], v199 offset:32768
	ds_read_b128 v[68:71], v199 offset:40960
	ds_read_b128 v[228:231], v200 offset:32768
	ds_read_b128 v[232:235], v200 offset:40960
	v_exp_f32_e32 v221, v221
	v_exp_f32_e32 v222, v222
	s_waitcnt lgkmcnt(3)
	v_mfma_f32_32x32x16_bf16 v[80:95], v[64:67], v[124:127], 0
	v_exp_f32_e32 v223, v223
	v_exp_f32_e32 v224, v224
	v_exp_f32_e32 v225, v225
	s_waitcnt lgkmcnt(2)
	v_mfma_f32_32x32x16_bf16 v[64:79], v[68:71], v[124:127], 0
	v_exp_f32_e32 v214, v214
	v_exp_f32_e32 v215, v215
	v_exp_f32_e32 v216, v216
	s_waitcnt lgkmcnt(1)
	v_mfma_f32_32x32x16_bf16 v[80:95], v[228:231], v[120:123], v[80:95]
	v_exp_f32_e32 v217, v217
	v_exp_f32_e32 v218, v218
	v_exp_f32_e32 v219, v219
	s_waitcnt lgkmcnt(0)
	v_mfma_f32_32x32x16_bf16 v[64:79], v[232:235], v[120:123], v[64:79]
	ds_read_b128 v[228:231], v201 offset:32768
	ds_read_b128 v[232:235], v201 offset:40960
	v_exp_f32_e32 v220, v220
	v_exp_f32_e32 v226, v226
	v_exp_f32_e32 v227, v227
	s_waitcnt lgkmcnt(1)
	v_mfma_f32_32x32x16_bf16 v[80:95], v[228:231], v[116:119], v[80:95]
	v_exp_f32_e32 v253, v212
	v_exp_f32_e32 v252, v213
	v_add_f32_e32 v212, 0, v236
	v_add_f32_e32 v212, v237, v212
	s_waitcnt lgkmcnt(0)
	v_mfma_f32_32x32x16_bf16 v[64:79], v[232:235], v[116:119], v[64:79]
	ds_read_b128 v[228:231], v202 offset:32768
	ds_read_b128 v[232:235], v202 offset:40960
	v_add_f32_e32 v212, v238, v212
	v_add_f32_e32 v212, v239, v212
	v_add_f32_e32 v212, v240, v212
	v_add_f32_e32 v212, v241, v212
	v_add_f32_e32 v212, v242, v212
	v_add_f32_e32 v212, v243, v212
	s_waitcnt lgkmcnt(1)
	v_mfma_f32_32x32x16_bf16 v[80:95], v[228:231], v[112:115], v[80:95]
	v_add_f32_e32 v212, v244, v212
	v_add_f32_e32 v212, v245, v212
	v_add_f32_e32 v212, v246, v212
	v_add_f32_e32 v212, v247, v212
	v_add_f32_e32 v212, v248, v212
	v_add_f32_e32 v212, v249, v212
	s_waitcnt lgkmcnt(0)
	v_mfma_f32_32x32x16_bf16 v[64:79], v[232:235], v[112:115], v[64:79]
	ds_read_b128 v[228:231], v203 offset:32768
	ds_read_b128 v[232:235], v203 offset:40960
	v_add_f32_e32 v212, v250, v212
	v_add_f32_e32 v212, v251, v212
	v_add_f32_e32 v212, v221, v212
	v_add_f32_e32 v212, v222, v212
	v_add_f32_e32 v212, v223, v212
	v_add_f32_e32 v212, v224, v212
	s_waitcnt lgkmcnt(1)
	v_mfma_f32_32x32x16_bf16 v[80:95], v[228:231], v[108:111], v[80:95]
	v_add_f32_e32 v212, v225, v212
	v_add_f32_e32 v212, v214, v212
	v_add_f32_e32 v212, v215, v212
	v_add_f32_e32 v212, v216, v212
	v_add_f32_e32 v212, v217, v212
	v_add_f32_e32 v212, v218, v212
	s_waitcnt lgkmcnt(0)
	v_mfma_f32_32x32x16_bf16 v[64:79], v[232:235], v[108:111], v[64:79]
	ds_read_b128 v[228:231], v204 offset:32768
	ds_read_b128 v[232:235], v204 offset:40960
	v_add_f32_e32 v212, v219, v212
	v_add_f32_e32 v212, v220, v212
	v_add_f32_e32 v212, v252, v212
	v_add_f32_e32 v212, v226, v212
	v_add_f32_e32 v212, v227, v212
	v_add_f32_e32 v212, v253, v212
	s_waitcnt lgkmcnt(1)
	v_mfma_f32_32x32x16_bf16 v[80:95], v[228:231], v[104:107], v[80:95]
	v_mov_b32_e32 v213, v212
	v_cvt_pk_bf16_f32 v160, v236, v237
	v_cvt_pk_bf16_f32 v161, v238, v239
	v_cvt_pk_bf16_f32 v162, v240, v241
	v_cvt_pk_bf16_f32 v163, v242, v243
	v_cvt_pk_bf16_f32 v164, v244, v245
	s_waitcnt lgkmcnt(0)
	v_mfma_f32_32x32x16_bf16 v[64:79], v[232:235], v[104:107], v[64:79]
	ds_read_b128 v[228:231], v205 offset:32768
	ds_read_b128 v[232:235], v205 offset:40960
	v_cvt_pk_bf16_f32 v165, v246, v247
	v_cvt_pk_bf16_f32 v166, v248, v249
	v_cvt_pk_bf16_f32 v167, v250, v251
	v_cvt_pk_bf16_f32 v168, v221, v222
	v_cvt_pk_bf16_f32 v169, v223, v224
	v_cvt_pk_bf16_f32 v170, v225, v214
	s_waitcnt lgkmcnt(1)
	v_mfma_f32_32x32x16_bf16 v[80:95], v[228:231], v[100:103], v[80:95]
	v_cvt_pk_bf16_f32 v171, v215, v216
	v_cvt_pk_bf16_f32 v172, v217, v218
	v_cvt_pk_bf16_f32 v173, v219, v220
	v_cvt_pk_bf16_f32 v174, v252, v226
	v_cvt_pk_bf16_f32 v175, v227, v253
	v_permlane32_swap_b32_e32 v212, v213
	s_waitcnt lgkmcnt(0)
	v_mfma_f32_32x32x16_bf16 v[64:79], v[232:235], v[100:103], v[64:79]
	ds_read_b128 v[228:231], v206 offset:32768
	ds_read_b128 v[232:235], v206 offset:40960
	v_permlane32_swap_b32_e32 v160, v162
	v_permlane32_swap_b32_e32 v161, v163
	v_permlane32_swap_b32_e32 v164, v166
	v_permlane32_swap_b32_e32 v165, v167
	v_permlane32_swap_b32_e32 v168, v170
	v_permlane32_swap_b32_e32 v169, v171
	s_waitcnt lgkmcnt(1)
	v_mfma_f32_32x32x16_bf16 v[80:95], v[228:231], v[96:99], v[80:95]
	v_permlane32_swap_b32_e32 v172, v174
	v_permlane32_swap_b32_e32 v173, v175
	s_waitcnt lgkmcnt(0)
	v_mfma_f32_32x32x16_bf16 v[64:79], v[232:235], v[96:99], v[64:79]
	s_cmpk_gt_u32 s61, 0x80
	s_cselect_b64 s[30:31], -1, 0
	s_and_b64 vcc, exec, s[30:31]
	s_cbranch_vccnz .LBB0_2129
	v_add_co_u32_e32 v132, vcc, 0xfffe8000, v184
	s_nop 1
	v_addc_co_u32_e32 v133, vcc, -1, v185, vcc
	global_load_dwordx4 v[128:131], v[132:133], off
	global_load_dwordx4 v[140:143], v[132:133], off offset:-512
	global_load_dwordx4 v[136:139], v[184:185], off
	s_nop 0
	global_load_dwordx4 v[132:135], v[184:185], off offset:-512
; #define SWRITE(b, i) do { *(LAS bf16x8*)(V_lds + (b) * SHM_V + vst0) = sr_[i].vs0;          \
;     *(LAS bf16x8*)(V_lds + (b) * SHM_V + vst1) = sr_[i].vs1; const int kc = sc * 2;               \
;     *(LAS bf16x8*)(K_lds + (b) * SHM_K + KSWZ(sr, kc)) = sr_[i].ks0;                       \
;     *(LAS bf16x8*)(K_lds + (b) * SHM_K + KSWZ(32 + sr, kc)) = sr_[i].ks1; } while (0)
; #define SWAIT() asm volatile("s_waitcnt vmcnt(4)" ::: "memory")
; #define RESC(a) do { if (__any((a) < 1.f)) { if (hi == 0) al_l[r32] = (a); asm volatile("s_waitcnt lgkmcnt(0)" ::: "memory"); \
;     _Pragma("unroll") for (int d = 0; d < NDV; ++d) _Pragma("unroll") for (int r = 0; r < 16; ++r) o[d][r] *= al_l[crow(r, hi)]; } } while (0)
; __device__ __forceinline__ void partialSM(f32x16& p0, f32x16& p1, float& m_reg, float& mn, float& alpha, float C, float thr) {
;   float pmax = p0[0];
; #pragma unroll
;   for (int r = 1; r < 16; ++r) pmax = fmaxf(pmax, p0[r]);
; #pragma unroll
;   for (int r = 0; r < 16; ++r) pmax = fmaxf(pmax, p1[r]);
;   { auto rr = __builtin_amdgcn_permlane32_swap(__float_as_uint(pmax), __float_as_uint(pmax), false, false);
;     pmax = fmaxf(__uint_as_float(rr[0]), __uint_as_float(rr[1])); }
;   if (__builtin_expect(__all(pmax - m_reg <= thr), 1)) { mn = m_reg; alpha = 1.f; }
;   else { mn = fmaxf(m_reg, pmax); alpha = __builtin_amdgcn_exp2f((m_reg - mn) * C); m_reg = mn; }
;   const float mnC = -mn * C;
; #pragma unroll
;   for (int r = 0; r < 16; ++r) p0[r] = fmaf(p0[r], C, mnC);
; #pragma unroll
;   for (int r = 0; r < 16; ++r) p1[r] = fmaf(p1[r], C, mnC);
; #pragma unroll
;   for (int r = 0; r < 16; ++r) p0[r] = __builtin_amdgcn_exp2f(p0[r]);
; template <int NDQ, int NDV> ...
;     ...
;     pv_d0<NDV>(o, vb0 + SHM_V, pa0, pa1, pa2, pa3); partialSM(pA0, pA1, m_reg, mnA, alA, Cs, thr);
;     __syncthreads(); SWAIT(); SWRITE(1, SO);
;     RESC(alA); __syncthreads();
.LBB0_2129:
	ds_read_b64_tr_b16 v[214:215], v193 offset:0
	ds_read_b64_tr_b16 v[216:217], v193 offset:0x800
	ds_read_b64_tr_b16 v[218:219], v193 offset:0x1000
	ds_read_b64_tr_b16 v[220:221], v193 offset:0x1800
	ds_read_b64_tr_b16 v[222:223], v193 offset:0x2000
	ds_read_b64_tr_b16 v[224:225], v193 offset:0x2800
	ds_read_b64_tr_b16 v[226:227], v193 offset:0x3000
	ds_read_b64_tr_b16 v[228:229], v193 offset:0x3800
	s_waitcnt lgkmcnt(6)
	v_mfma_f32_32x32x16_bf16 v[0:15], v[160:163], v[214:217], v[0:15]
	ds_read_b64_tr_b16 v[214:215], v193 offset:0x200
	ds_read_b64_tr_b16 v[216:217], v193 offset:0xa00
	v_max_f32_e32 v234, v81, v81
	v_max_f32_e32 v235, v80, v80
	v_max_f32_e32 v234, v235, v234
	v_max3_f32 v234, v234, v82, v83
	v_max3_f32 v234, v234, v84, v85
	v_max3_f32 v234, v234, v86, v87
	s_waitcnt lgkmcnt(6)
	v_mfma_f32_32x32x16_bf16 v[0:15], v[164:167], v[218:221], v[0:15]
	ds_read_b64_tr_b16 v[218:219], v193 offset:0x1200
	ds_read_b64_tr_b16 v[220:221], v193 offset:0x1a00
	v_max3_f32 v234, v234, v88, v89
	v_max3_f32 v234, v234, v90, v91
	v_max3_f32 v234, v234, v92, v93
	v_max3_f32 v234, v234, v94, v95
	v_max3_f32 v234, v234, v64, v65
	v_max3_f32 v234, v234, v66, v67
	s_waitcnt lgkmcnt(6)
	v_mfma_f32_32x32x16_bf16 v[0:15], v[168:171], v[222:225], v[0:15]
	ds_read_b64_tr_b16 v[222:223], v193 offset:0x2200
	ds_read_b64_tr_b16 v[224:225], v193 offset:0x2a00
	ds_read_b64_tr_b16 v[230:231], v193 offset:0x3200
	ds_read_b64_tr_b16 v[232:233], v193 offset:0x3a00
	v_max3_f32 v234, v234, v68, v69
	v_max3_f32 v234, v234, v70, v71
	v_max3_f32 v234, v234, v72, v73
	v_max3_f32 v234, v234, v74, v75
	v_max3_f32 v234, v234, v76, v77
	v_max3_f32 v234, v234, v78, v79
	s_waitcnt lgkmcnt(8)
	v_mfma_f32_32x32x16_bf16 v[0:15], v[172:175], v[226:229], v[0:15]
	v_mov_b32_e32 v235, v234
	s_nop 1
	v_permlane32_swap_b32_e32 v234, v235
	v_max_f32_e32 v235, v235, v235
	v_max_f32_e32 v234, v234, v234
	v_max_f32_e32 v234, v234, v235
	s_waitcnt lgkmcnt(6)
	v_mfma_f32_32x32x16_bf16 v[48:63], v[160:163], v[214:217], v[48:63]
	ds_read_b64_tr_b16 v[214:215], v193 offset:0x400
	ds_read_b64_tr_b16 v[216:217], v193 offset:0xc00
	v_max_f32_e32 v253, v211, v211
	v_sub_f32_e32 v235, v234, v211
	v_max_f32_e32 v234, v253, v234
	v_sub_f32_e32 v253, v211, v234
	v_mul_f32_e32 v253, 0x3e0293ee, v253
	s_waitcnt lgkmcnt(6)
	v_mfma_f32_32x32x16_bf16 v[48:63], v[164:167], v[218:221], v[48:63]
	ds_read_b64_tr_b16 v[218:219], v193 offset:0x1400
	ds_read_b64_tr_b16 v[220:221], v193 offset:0x1c00
	v_exp_f32_e32 v253, v253
	v_cmp_ge_f32_e32 vcc, s48, v235
	s_cmp_eq_u64 vcc, exec
	s_cselect_b64 s[2:3], -1, 0
	v_cndmask_b32_e64 v234, v234, v211, s[2:3]
	s_waitcnt lgkmcnt(6)
	v_mfma_f32_32x32x16_bf16 v[48:63], v[168:171], v[222:225], v[48:63]
	ds_read_b64_tr_b16 v[222:223], v193 offset:0x2400
	ds_read_b64_tr_b16 v[224:225], v193 offset:0x2c00
	ds_read_b64_tr_b16 v[226:227], v193 offset:0x3400
	ds_read_b64_tr_b16 v[228:229], v193 offset:0x3c00
	v_mul_f32_e32 v252, 0xbe0293ee, v234
	v_fmamk_f32 v80, v80, 0x3e0293ee, v252
	v_fmamk_f32 v81, v81, 0x3e0293ee, v252
	v_fmamk_f32 v82, v82, 0x3e0293ee, v252
	v_fmamk_f32 v83, v83, 0x3e0293ee, v252
	v_fmamk_f32 v84, v84, 0x3e0293ee, v252
	s_waitcnt lgkmcnt(8)
	v_mfma_f32_32x32x16_bf16 v[48:63], v[172:175], v[230:233], v[48:63]
	v_fmamk_f32 v85, v85, 0x3e0293ee, v252
	v_fmamk_f32 v86, v86, 0x3e0293ee, v252
	v_fmamk_f32 v87, v87, 0x3e0293ee, v252
	v_fmamk_f32 v88, v88, 0x3e0293ee, v252
	v_fmamk_f32 v89, v89, 0x3e0293ee, v252
	v_fmamk_f32 v90, v90, 0x3e0293ee, v252
	s_waitcnt lgkmcnt(6)
	v_mfma_f32_32x32x16_bf16 v[32:47], v[160:163], v[214:217], v[32:47]
	ds_read_b64_tr_b16 v[214:215], v193 offset:0x600
	ds_read_b64_tr_b16 v[216:217], v193 offset:0xe00
	v_fmamk_f32 v91, v91, 0x3e0293ee, v252
	v_fmamk_f32 v92, v92, 0x3e0293ee, v252
	v_fmamk_f32 v93, v93, 0x3e0293ee, v252
	v_fmamk_f32 v94, v94, 0x3e0293ee, v252
	v_fmamk_f32 v95, v95, 0x3e0293ee, v252
	s_waitcnt lgkmcnt(6)
	v_mfma_f32_32x32x16_bf16 v[32:47], v[164:167], v[218:221], v[32:47]
	ds_read_b64_tr_b16 v[218:219], v193 offset:0x1600
	ds_read_b64_tr_b16 v[220:221], v193 offset:0x1e00
	v_exp_f32_e32 v236, v80
	v_exp_f32_e32 v237, v81
	v_exp_f32_e32 v238, v82
	s_waitcnt lgkmcnt(6)
	v_mfma_f32_32x32x16_bf16 v[32:47], v[168:171], v[222:225], v[32:47]
	ds_read_b64_tr_b16 v[222:223], v193 offset:0x2600
	ds_read_b64_tr_b16 v[224:225], v193 offset:0x2e00
	ds_read_b64_tr_b16 v[230:231], v193 offset:0x3600
	ds_read_b64_tr_b16 v[232:233], v193 offset:0x3e00
	v_exp_f32_e32 v239, v83
	v_exp_f32_e32 v240, v84
	v_exp_f32_e32 v241, v85
	s_waitcnt lgkmcnt(8)
	v_mfma_f32_32x32x16_bf16 v[32:47], v[172:175], v[226:229], v[32:47]
	v_exp_f32_e32 v242, v86
	v_exp_f32_e32 v243, v87
	v_exp_f32_e32 v244, v88
	s_waitcnt lgkmcnt(6)
	v_mfma_f32_32x32x16_bf16 v[16:31], v[160:163], v[214:217], v[16:31]
	v_exp_f32_e32 v245, v89
	v_exp_f32_e32 v246, v90
	v_exp_f32_e32 v247, v91
	s_waitcnt lgkmcnt(4)
	v_mfma_f32_32x32x16_bf16 v[16:31], v[164:167], v[218:221], v[16:31]
	v_exp_f32_e32 v248, v92
	v_exp_f32_e32 v249, v93
	v_exp_f32_e32 v250, v94
	s_waitcnt lgkmcnt(2)
	v_mfma_f32_32x32x16_bf16 v[16:31], v[168:171], v[222:225], v[16:31]
	v_exp_f32_e32 v251, v95
	s_waitcnt lgkmcnt(0)
	v_mfma_f32_32x32x16_bf16 v[16:31], v[172:175], v[230:233], v[16:31]
	s_barrier
	s_waitcnt vmcnt(4)
	s_cmp_lg_u64 s[30:31], 0
	s_cbranch_scc0 .Lgqa_nodrain
	s_waitcnt vmcnt(0)
; #define SBAR() __builtin_amdgcn_sched_barrier(0)
; template <int NDQ, int NDV> ...
;     ...
;   SBAR(); qkt<NDQ>(pB0, pB1, K_lds + SHM_K, qr, r32, hi);
;   finishSM(pA0, pA1, alA, l_reg, pa0, pa1, pa2, pa3); SBAR();
;   pv_d0<NDV>(o, vb0, pa0, pa1, pa2, pa3); partialSM(pB0, pB1, m_reg, mnB, alB, Cs, thr);
.Lgqa_nodrain:
	v_cndmask_b32_e64 v161, v253, 1.0, s[2:3]
	v_cmp_gt_f32_e32 vcc, 1.0, v161
	ds_write_b128 v197, v[144:147] offset:16384
	ds_write_b128 v198, v[156:159] offset:16384
	ds_write_b128 v195, v[148:151] offset:49152
	ds_write_b128 v196, v[152:155] offset:49152
	s_cbranch_vccz .LBB0_2133
	s_and_saveexec_b64 s[36:37], s[0:1]
	ds_write_b32 v191, v161 offset:128
	s_or_b64 exec, exec, s[36:37]
	s_waitcnt lgkmcnt(0)
	v_add_u32_e32 v156, v183, v176
	ds_read_b128 v[144:147], v156 offset:224
	ds_read_b128 v[148:151], v156 offset:192
	ds_read_b128 v[152:155], v156 offset:160
	ds_read_b128 v[156:159], v156 offset:128
	s_waitcnt lgkmcnt(3)
	v_pk_mul_f32 v[12:13], v[12:13], v[144:145]
	s_waitcnt lgkmcnt(2)
	v_pk_mul_f32 v[8:9], v[8:9], v[148:149]
	s_waitcnt lgkmcnt(1)
	v_pk_mul_f32 v[4:5], v[4:5], v[152:153]
	v_pk_mul_f32 v[14:15], v[14:15], v[146:147]
	v_pk_mul_f32 v[10:11], v[10:11], v[150:151]
	v_pk_mul_f32 v[6:7], v[6:7], v[154:155]
	s_waitcnt lgkmcnt(0)
	v_pk_mul_f32 v[2:3], v[2:3], v[158:159]
	v_pk_mul_f32 v[0:1], v[0:1], v[156:157]
	v_pk_mul_f32 v[60:61], v[60:61], v[144:145]
	v_pk_mul_f32 v[56:57], v[56:57], v[148:149]
	v_pk_mul_f32 v[52:53], v[52:53], v[152:153]
	v_pk_mul_f32 v[62:63], v[62:63], v[146:147]
	v_pk_mul_f32 v[58:59], v[58:59], v[150:151]
	v_pk_mul_f32 v[54:55], v[54:55], v[154:155]
	v_pk_mul_f32 v[50:51], v[50:51], v[158:159]
	v_pk_mul_f32 v[48:49], v[48:49], v[156:157]
	v_pk_mul_f32 v[44:45], v[44:45], v[144:145]
	v_pk_mul_f32 v[40:41], v[40:41], v[148:149]
	v_pk_mul_f32 v[36:37], v[36:37], v[152:153]
	v_pk_mul_f32 v[46:47], v[46:47], v[146:147]
	v_pk_mul_f32 v[42:43], v[42:43], v[150:151]
	v_pk_mul_f32 v[38:39], v[38:39], v[154:155]
	v_pk_mul_f32 v[34:35], v[34:35], v[158:159]
	v_pk_mul_f32 v[32:33], v[32:33], v[156:157]
	v_pk_mul_f32 v[28:29], v[28:29], v[144:145]
	v_pk_mul_f32 v[24:25], v[24:25], v[148:149]
	v_pk_mul_f32 v[20:21], v[20:21], v[152:153]
	v_pk_mul_f32 v[30:31], v[30:31], v[146:147]
	v_pk_mul_f32 v[26:27], v[26:27], v[150:151]
	v_pk_mul_f32 v[22:23], v[22:23], v[154:155]
	v_pk_mul_f32 v[18:19], v[18:19], v[158:159]
	v_pk_mul_f32 v[16:17], v[16:17], v[156:157]
.LBB0_2133:
	v_mov_b32_e32 v160, v234
	v_pk_fma_f32 v[154:155], v[64:65], s[4:5], v[252:253] op_sel_hi:[1,0,0]
	v_add_f32_e32 v64, v208, v209
	v_fmac_f32_e32 v64, v207, v192
	v_add_f32_e32 v192, v212, v213
	v_pk_fma_f32 v[152:153], v[66:67], s[4:5], v[252:253] op_sel_hi:[1,0,0]
	v_pk_fma_f32 v[148:149], v[68:69], s[4:5], v[252:253] op_sel_hi:[1,0,0]
	v_pk_fma_f32 v[146:147], v[70:71], s[4:5], v[252:253] op_sel_hi:[1,0,0]
	v_pk_fma_f32 v[144:145], v[72:73], s[4:5], v[252:253] op_sel_hi:[1,0,0]
	v_pk_fma_f32 v[158:159], v[74:75], s[4:5], v[252:253] op_sel_hi:[1,0,0]
	v_pk_fma_f32 v[156:157], v[76:77], s[4:5], v[252:253] op_sel_hi:[1,0,0]
	v_pk_fma_f32 v[150:151], v[78:79], s[4:5], v[252:253] op_sel_hi:[1,0,0]
	v_fmac_f32_e32 v192, v64, v210
	v_lshl_add_u64 v[184:185], v[184:185], 0, s[6:7]
	s_and_b64 vcc, exec, s[30:31]
	s_waitcnt lgkmcnt(0)
	s_barrier
	s_cbranch_vccnz .LBB0_2135
	v_mov_b32_e32 v207, v161
	s_branch .LBB0_2123
.LBB0_2135:
	v_mov_b32_e32 v175, v236
	v_mov_b32_e32 v214, v237
	v_mov_b32_e32 v173, v238
	v_mov_b32_e32 v211, v239
	v_mov_b32_e32 v172, v240
	v_mov_b32_e32 v174, v241
	v_mov_b32_e32 v170, v242
	v_mov_b32_e32 v171, v243
	v_mov_b32_e32 v167, v244
	v_mov_b32_e32 v169, v245
	v_mov_b32_e32 v166, v246
	v_mov_b32_e32 v168, v247
	v_mov_b32_e32 v163, v248
	v_mov_b32_e32 v165, v249
	v_mov_b32_e32 v162, v250
	v_mov_b32_e32 v164, v251
	ds_read_b128 v[64:67], v199 offset:49152
	ds_read_b128 v[68:71], v199 offset:57344
	v_exp_f32_e32 v154, v154
	v_exp_f32_e32 v155, v155
	v_exp_f32_e32 v152, v152
	s_waitcnt lgkmcnt(1)
	v_mfma_f32_32x32x16_bf16 v[80:95], v[64:67], v[124:127], 0
	v_exp_f32_e32 v153, v153
	v_exp_f32_e32 v148, v148
	s_waitcnt lgkmcnt(0)
	v_mfma_f32_32x32x16_bf16 v[64:79], v[68:71], v[124:127], 0
	ds_read_b128 v[124:127], v200 offset:49152
	ds_read_b128 v[128:131], v200 offset:57344
	ds_read_b128 v[132:135], v201 offset:49152
	ds_read_b128 v[136:139], v201 offset:57344
	s_waitcnt lgkmcnt(3)
	v_mfma_f32_32x32x16_bf16 v[80:95], v[124:127], v[120:123], v[80:95]
	ds_read_b128 v[124:127], v202 offset:49152
	ds_read_b128 v[140:143], v202 offset:57344
	ds_read_b128 v[196:199], v203 offset:49152
	ds_read_b128 v[200:203], v203 offset:57344
	ds_read_b128 v[216:219], v204 offset:49152
	ds_read_b128 v[220:223], v204 offset:57344
	ds_read_b128 v[224:227], v205 offset:49152
	ds_read_b128 v[228:231], v205 offset:57344
	s_waitcnt lgkmcnt(10)
	v_mfma_f32_32x32x16_bf16 v[64:79], v[128:131], v[120:123], v[64:79]
	ds_read_b128 v[120:123], v206 offset:49152
	ds_read_b128 v[128:131], v206 offset:57344
	s_waitcnt lgkmcnt(11)
	v_mfma_f32_32x32x16_bf16 v[80:95], v[132:135], v[116:119], v[80:95]
	v_exp_f32_e32 v132, v149
	v_exp_f32_e32 v133, v146
	v_exp_f32_e32 v134, v147
	v_exp_f32_e32 v135, v144
	v_exp_f32_e32 v144, v145
	v_exp_f32_e32 v145, v158
	v_exp_f32_e32 v146, v159
	s_waitcnt lgkmcnt(10)
	v_mfma_f32_32x32x16_bf16 v[64:79], v[136:139], v[116:119], v[64:79]
	v_add_f32_e32 v116, 0, v175
	v_add_f32_e32 v116, v214, v116
	v_add_f32_e32 v116, v173, v116
	v_add_f32_e32 v116, v211, v116
	v_add_f32_e32 v116, v172, v116
	v_add_f32_e32 v116, v174, v116
	v_add_f32_e32 v116, v170, v116
	s_waitcnt lgkmcnt(9)
	v_mfma_f32_32x32x16_bf16 v[80:95], v[124:127], v[112:115], v[80:95]
	v_add_f32_e32 v116, v171, v116
	v_add_f32_e32 v116, v167, v116
	v_add_f32_e32 v116, v169, v116
	v_exp_f32_e32 v118, v156
	v_exp_f32_e32 v119, v157
	v_exp_f32_e32 v136, v150
	v_exp_f32_e32 v137, v151
	s_waitcnt lgkmcnt(8)
; #define SBAR() __builtin_amdgcn_sched_barrier(0)
; #define RESC(a) do { if (__any((a) < 1.f)) { if (hi == 0) al_l[r32] = (a); asm volatile("s_waitcnt lgkmcnt(0)" ::: "memory"); \
;     _Pragma("unroll") for (int d = 0; d < NDV; ++d) _Pragma("unroll") for (int r = 0; r < 16; ++r) o[d][r] *= al_l[crow(r, hi)]; } } while (0)
; __device__ __forceinline__ void partialSM(f32x16& p0, f32x16& p1, float& m_reg, float& mn, float& alpha, float C, float thr) {
;   float pmax = p0[0];
; #pragma unroll
;   for (int r = 1; r < 16; ++r) pmax = fmaxf(pmax, p0[r]);
; #pragma unroll
;   for (int r = 0; r < 16; ++r) pmax = fmaxf(pmax, p1[r]);
;   { auto rr = __builtin_amdgcn_permlane32_swap(__float_as_uint(pmax), __float_as_uint(pmax), false, false);
;     pmax = fmaxf(__uint_as_float(rr[0]), __uint_as_float(rr[1])); }
;   if (__builtin_expect(__all(pmax - m_reg <= thr), 1)) { mn = m_reg; alpha = 1.f; }
;   else { mn = fmaxf(m_reg, pmax); alpha = __builtin_amdgcn_exp2f((m_reg - mn) * C); m_reg = mn; }
; template <int NDQ, int NDV> ...
;     ...
;   finishSM(pA0, pA1, alA, l_reg, pa0, pa1, pa2, pa3); SBAR();
;   pv_d0<NDV>(o, vb0, pa0, pa1, pa2, pa3); partialSM(pB0, pB1, m_reg, mnB, alB, Cs, thr);
;   __syncthreads(); RESC(alB);
	v_mfma_f32_32x32x16_bf16 v[64:79], v[140:143], v[112:115], v[64:79]
	v_add_f32_e32 v112, v166, v116
	v_add_f32_e32 v112, v168, v112
	v_add_f32_e32 v112, v163, v112
	v_add_f32_e32 v112, v165, v112
	v_add_f32_e32 v112, v162, v112
	v_add_f32_e32 v112, v164, v112
	v_add_f32_e32 v112, v154, v112
	s_waitcnt lgkmcnt(7)
	v_mfma_f32_32x32x16_bf16 v[80:95], v[196:199], v[108:111], v[80:95]
	v_add_f32_e32 v112, v155, v112
	v_add_f32_e32 v112, v152, v112
	v_add_f32_e32 v112, v153, v112
	v_add_f32_e32 v112, v148, v112
	v_add_f32_e32 v112, v132, v112
	v_add_f32_e32 v112, v133, v112
	v_add_f32_e32 v112, v134, v112
	s_waitcnt lgkmcnt(6)
	v_mfma_f32_32x32x16_bf16 v[64:79], v[200:203], v[108:111], v[64:79]
	v_add_f32_e32 v108, v135, v112
	v_add_f32_e32 v108, v144, v108
	v_add_f32_e32 v108, v145, v108
	v_add_f32_e32 v108, v146, v108
	v_add_f32_e32 v108, v118, v108
	v_add_f32_e32 v108, v119, v108
	v_add_f32_e32 v108, v136, v108
	s_waitcnt lgkmcnt(5)
	v_mfma_f32_32x32x16_bf16 v[80:95], v[216:219], v[104:107], v[80:95]
	v_add_f32_e32 v108, v137, v108
	v_mov_b32_e32 v109, v108
	s_nop 1
	v_permlane32_swap_b32_e32 v108, v109
	v_cvt_pk_bf16_f32 v110, v175, v214
	v_cvt_pk_bf16_f32 v111, v173, v211
	v_cvt_pk_bf16_f32 v112, v172, v174
	s_waitcnt lgkmcnt(4)
	v_mfma_f32_32x32x16_bf16 v[64:79], v[220:223], v[104:107], v[64:79]
	v_cvt_pk_bf16_f32 v113, v170, v171
	v_cvt_pk_bf16_f32 v104, v167, v169
	v_cvt_pk_bf16_f32 v105, v166, v168
	v_cvt_pk_bf16_f32 v106, v163, v165
	v_cvt_pk_bf16_f32 v107, v162, v164
	v_cvt_pk_bf16_f32 v114, v154, v155
	v_cvt_pk_bf16_f32 v115, v152, v153
	s_waitcnt lgkmcnt(3)
	v_mfma_f32_32x32x16_bf16 v[80:95], v[224:227], v[100:103], v[80:95]
	v_cvt_pk_bf16_f32 v116, v148, v132
	v_cvt_pk_bf16_f32 v117, v133, v134
	v_permlane32_swap_b32_e32 v110, v112
	v_permlane32_swap_b32_e32 v111, v113
	v_permlane32_swap_b32_e32 v104, v106
	s_waitcnt lgkmcnt(2)
	v_mfma_f32_32x32x16_bf16 v[64:79], v[228:231], v[100:103], v[64:79]
	v_cvt_pk_bf16_f32 v100, v135, v144
	v_cvt_pk_bf16_f32 v101, v145, v146
	v_cvt_pk_bf16_f32 v102, v118, v119
	v_cvt_pk_bf16_f32 v103, v136, v137
	v_permlane32_swap_b32_e32 v105, v107
	v_permlane32_swap_b32_e32 v114, v116
	s_waitcnt lgkmcnt(1)
	v_mfma_f32_32x32x16_bf16 v[80:95], v[120:123], v[96:99], v[80:95]
	v_permlane32_swap_b32_e32 v115, v117
	v_permlane32_swap_b32_e32 v100, v102
	v_permlane32_swap_b32_e32 v101, v103
	s_waitcnt lgkmcnt(0)
	v_mfma_f32_32x32x16_bf16 v[64:79], v[128:131], v[96:99], v[64:79]
	ds_read_b64_tr_b16 v[96:97], v194 offset:0
	ds_read_b64_tr_b16 v[98:99], v194 offset:0x800
	ds_read_b64_tr_b16 v[118:119], v194 offset:0x1000
	ds_read_b64_tr_b16 v[120:121], v194 offset:0x1800
	ds_read_b64_tr_b16 v[122:123], v194 offset:0x2000
	ds_read_b64_tr_b16 v[124:125], v194 offset:0x2800
	ds_read_b64_tr_b16 v[126:127], v194 offset:0x3000
	ds_read_b64_tr_b16 v[128:129], v194 offset:0x3800
	s_waitcnt lgkmcnt(0)
	s_nop 0
	v_mfma_f32_32x32x16_bf16 v[0:15], v[110:113], v[96:99], v[0:15]
	ds_read_b64_tr_b16 v[96:97], v194 offset:0x200
	ds_read_b64_tr_b16 v[98:99], v194 offset:0xa00
	v_mfma_f32_32x32x16_bf16 v[0:15], v[104:107], v[118:121], v[0:15]
	ds_read_b64_tr_b16 v[118:119], v194 offset:0x1200
	ds_read_b64_tr_b16 v[120:121], v194 offset:0x1a00
	v_mfma_f32_32x32x16_bf16 v[0:15], v[114:117], v[122:125], v[0:15]
	ds_read_b64_tr_b16 v[122:123], v194 offset:0x2200
	ds_read_b64_tr_b16 v[124:125], v194 offset:0x2a00
	ds_read_b64_tr_b16 v[130:131], v194 offset:0x3200
	ds_read_b64_tr_b16 v[132:133], v194 offset:0x3a00
	s_waitcnt lgkmcnt(0)
	v_mfma_f32_32x32x16_bf16 v[0:15], v[100:103], v[126:129], v[0:15]
	v_mfma_f32_32x32x16_bf16 v[48:63], v[110:113], v[96:99], v[48:63]
	ds_read_b64_tr_b16 v[96:97], v194 offset:0x400
	ds_read_b64_tr_b16 v[98:99], v194 offset:0xc00
	v_mfma_f32_32x32x16_bf16 v[48:63], v[104:107], v[118:121], v[48:63]
	ds_read_b64_tr_b16 v[118:119], v194 offset:0x1400
	ds_read_b64_tr_b16 v[120:121], v194 offset:0x1c00
	v_mfma_f32_32x32x16_bf16 v[48:63], v[114:117], v[122:125], v[48:63]
	ds_read_b64_tr_b16 v[122:123], v194 offset:0x2400
	ds_read_b64_tr_b16 v[124:125], v194 offset:0x2c00
	ds_read_b64_tr_b16 v[126:127], v194 offset:0x3400
	ds_read_b64_tr_b16 v[128:129], v194 offset:0x3c00
	s_waitcnt lgkmcnt(0)
	v_mfma_f32_32x32x16_bf16 v[48:63], v[100:103], v[130:133], v[48:63]
	v_mfma_f32_32x32x16_bf16 v[32:47], v[110:113], v[96:99], v[32:47]
	ds_read_b64_tr_b16 v[96:97], v194 offset:0x600
	ds_read_b64_tr_b16 v[98:99], v194 offset:0xe00
	v_mfma_f32_32x32x16_bf16 v[32:47], v[104:107], v[118:121], v[32:47]
	ds_read_b64_tr_b16 v[118:119], v194 offset:0x1600
	ds_read_b64_tr_b16 v[120:121], v194 offset:0x1e00
	v_mfma_f32_32x32x16_bf16 v[32:47], v[114:117], v[122:125], v[32:47]
	ds_read_b64_tr_b16 v[122:123], v194 offset:0x2600
	ds_read_b64_tr_b16 v[124:125], v194 offset:0x2e00
	ds_read_b64_tr_b16 v[130:131], v194 offset:0x3600
	ds_read_b64_tr_b16 v[132:133], v194 offset:0x3e00
	s_waitcnt lgkmcnt(0)
	v_mfma_f32_32x32x16_bf16 v[32:47], v[100:103], v[126:129], v[32:47]
	v_mfma_f32_32x32x16_bf16 v[16:31], v[110:113], v[96:99], v[16:31]
	v_max_f32_e32 v126, v81, v81
	v_max_f32_e32 v127, v80, v80
	v_max_f32_e32 v126, v127, v126
	v_max3_f32 v126, v126, v82, v83
	v_max3_f32 v126, v126, v84, v85
	v_max3_f32 v96, v126, v86, v87
	v_max3_f32 v96, v96, v88, v89
	v_max3_f32 v96, v96, v90, v91
	v_mfma_f32_32x32x16_bf16 v[16:31], v[104:107], v[118:121], v[16:31]
	v_max3_f32 v96, v96, v92, v93
	v_max3_f32 v96, v96, v94, v95
	v_max3_f32 v96, v96, v64, v65
	v_max3_f32 v96, v96, v66, v67
	v_max3_f32 v96, v96, v68, v69
	v_max3_f32 v96, v96, v70, v71
	v_max3_f32 v96, v96, v72, v73
	v_max3_f32 v96, v96, v74, v75
	v_mfma_f32_32x32x16_bf16 v[16:31], v[114:117], v[122:125], v[16:31]
	v_max3_f32 v96, v96, v76, v77
	v_max3_f32 v96, v96, v78, v79
	v_mov_b32_e32 v97, v96
	s_nop 1
	v_permlane32_swap_b32_e32 v96, v97
	v_max_f32_e32 v97, v97, v97
	v_max_f32_e32 v96, v96, v96
	v_max_f32_e32 v96, v96, v97
	v_max_f32_e32 v97, v160, v160
	v_max_f32_e32 v97, v97, v96
	v_sub_f32_e32 v98, v96, v160
	v_mfma_f32_32x32x16_bf16 v[16:31], v[100:103], v[130:133], v[16:31]
	v_sub_f32_e32 v96, v160, v97
	v_mul_f32_e32 v96, 0x3e0293ee, v96
	v_exp_f32_e32 v96, v96
	v_cmp_ge_f32_e32 vcc, s48, v98
	s_cmp_eq_u64 vcc, exec
	s_cselect_b64 s[2:3], -1, 0
	v_cndmask_b32_e64 v96, v96, 1.0, s[2:3]
	v_cmp_gt_f32_e32 vcc, 1.0, v96
	s_barrier
; #define RESC(a) do { if (__any((a) < 1.f)) { if (hi == 0) al_l[r32] = (a); asm volatile("s_waitcnt lgkmcnt(0)" ::: "memory"); \
;     _Pragma("unroll") for (int d = 0; d < NDV; ++d) _Pragma("unroll") for (int r = 0; r < 16; ++r) o[d][r] *= al_l[crow(r, hi)]; } } while (0)
; template <int NDQ, int NDV> ...
;     ...
;   __syncthreads(); RESC(alB);
	s_cbranch_vccz .LBB0_2139
	s_and_saveexec_b64 s[30:31], s[0:1]
	ds_write_b32 v191, v96 offset:128
	s_or_b64 exec, exec, s[30:31]
	s_waitcnt lgkmcnt(0)
	v_add_u32_e32 v106, v183, v176
	ds_read_b128 v[98:101], v106 offset:224
	ds_read_b128 v[102:105], v106 offset:192
	ds_read_b128 v[110:113], v106 offset:160
	ds_read_b128 v[114:117], v106 offset:128
	s_waitcnt lgkmcnt(3)
	v_pk_mul_f32 v[12:13], v[12:13], v[98:99]
	s_waitcnt lgkmcnt(2)
	v_pk_mul_f32 v[8:9], v[8:9], v[102:103]
	s_waitcnt lgkmcnt(1)
	v_pk_mul_f32 v[4:5], v[4:5], v[110:111]
	v_pk_mul_f32 v[14:15], v[14:15], v[100:101]
	v_pk_mul_f32 v[10:11], v[10:11], v[104:105]
	v_pk_mul_f32 v[6:7], v[6:7], v[112:113]
	s_waitcnt lgkmcnt(0)
	v_pk_mul_f32 v[2:3], v[2:3], v[116:117]
	v_pk_mul_f32 v[0:1], v[0:1], v[114:115]
	v_pk_mul_f32 v[60:61], v[60:61], v[98:99]
	v_pk_mul_f32 v[56:57], v[56:57], v[102:103]
	v_pk_mul_f32 v[52:53], v[52:53], v[110:111]
	v_pk_mul_f32 v[62:63], v[62:63], v[100:101]
	v_pk_mul_f32 v[58:59], v[58:59], v[104:105]
	v_pk_mul_f32 v[54:55], v[54:55], v[112:113]
	v_pk_mul_f32 v[50:51], v[50:51], v[116:117]
	v_pk_mul_f32 v[48:49], v[48:49], v[114:115]
	v_pk_mul_f32 v[44:45], v[44:45], v[98:99]
	v_pk_mul_f32 v[40:41], v[40:41], v[102:103]
	v_pk_mul_f32 v[36:37], v[36:37], v[110:111]
	v_pk_mul_f32 v[46:47], v[46:47], v[100:101]
	v_pk_mul_f32 v[42:43], v[42:43], v[104:105]
	v_pk_mul_f32 v[38:39], v[38:39], v[112:113]
	v_pk_mul_f32 v[34:35], v[34:35], v[116:117]
	v_pk_mul_f32 v[32:33], v[32:33], v[114:115]
	v_pk_mul_f32 v[28:29], v[28:29], v[98:99]
	v_pk_mul_f32 v[24:25], v[24:25], v[102:103]
	v_pk_mul_f32 v[20:21], v[20:21], v[110:111]
	v_pk_mul_f32 v[30:31], v[30:31], v[100:101]
	v_pk_mul_f32 v[26:27], v[26:27], v[104:105]
	v_pk_mul_f32 v[22:23], v[22:23], v[112:113]
	v_pk_mul_f32 v[18:19], v[18:19], v[116:117]
	v_pk_mul_f32 v[16:17], v[16:17], v[114:115]
